# v063 + the same hoist in the layer-0 out-projection epilogue (16 loads ahead of the drain, vmcnt(16))
# baseline (speedup 1.0000x reference)
; #define PG8_WAIT_V(n) asm volatile("s_waitcnt vmcnt(" #n ")" ::: "memory")
; #define PG8_BAR __builtin_amdgcn_s_barrier()
; __device__ __forceinline__ float bf_lo(unsigned w) { return __uint_as_float(w << 16); }
; __device__ __forceinline__ float bf_hi(unsigned w) { return __uint_as_float(w & 0xffff0000u); }
; template <class Epi, class Sched, bool ALIGN_EPI = false, bool SP2 = false, bool PAIR_ACC = false>
; __device__ __forceinline__ void gemm_phase(PG8_LAS unsigned char* lds, const Gemm g, const Sched& S, const Epi& E) {
;     ...
;     PG8_WAIT_V(0);
;     if constexpr (!ALIGN_EPI) { if (wr == 0) PG8_BAR; }
;     PG8_BAR;
;     __device__ __forceinline__ void fused(f32x4 (&acc)[2][2][4][2], const Unit& u, int wr, int wc, int fr, int fq, PG8_LAS unsigned char* lds, int wid, int lane) const {
;     ...
;         const int col0 = u.pn * BM + wc * 32 + 8 * fq, b = u.pm >> 4;
;         {
;             f32x4 gv[2][2];
; #pragma unroll
;             for (int bj = 0; bj < 2; ++bj)
; #pragma unroll
;                 for (int n = 0; n < 2; ++n) gv[bj][n] = *(const f32x4*)(g + (size_t)b * 6144 + col0 + bj * HALF + 4 * n);
; #pragma unroll
;             for (int ai = 0; ai < 2; ++ai)
; #pragma unroll
;                 for (int m = 0; m < 4; ++m) { const int r = ai * HALF + wr * 64 + m * 16 + fr; const size_t off = (size_t)(u.pm * BM + r) * 1024 + col0;
; #pragma unroll
;                     for (int bj = 0; bj < 2; ++bj) { f32x4 b0, b1;
;                         if (XIN_BF16) { const u32x4 w = *(const u32x4*)((const bf16_t*)xin + off + bj * HALF); b0 = (f32x4){bf_lo(w.x), bf_hi(w.x), bf_lo(w.y), bf_hi(w.y)}; b1 = (f32x4){bf_lo(w.z), bf_hi(w.z), bf_lo(w.w), bf_hi(w.w)}; }
;                         else { b0 = *(const f32x4*)((const float*)xin + off + bj * HALF); b1 = *(const f32x4*)((const float*)xin + off + bj * HALF + 4); }
;                         acc[ai][bj][m][0] = b0 + gv[bj][0] * acc[ai][bj][m][0]; acc[ai][bj][m][1] = b1 + gv[bj][1] * acc[ai][bj][m][1]; }
.LBB0_730:
	s_lshl_b32 s6, s17, 5
	s_lshl_b32 s7, s10, 8
	v_lshrrev_b32_e32 v130, 1, v166
	s_or_b32 s6, s7, s6
	v_and_or_b32 v156, v130, 24, s6
	s_ashr_i32 s6, s16, 4
	s_mul_i32 s25, s6, 0x6000
	s_mul_hi_i32 s24, s6, 0x6000
	s_add_u32 s6, s12, s25
	s_addc_u32 s7, s13, s24
	s_lshl_b32 s30, s16, 8
	v_ashrrev_i32_e32 v157, 31, v156
	v_add_u32_e32 v154, s30, v170
	v_lshlrev_b64 v[158:159], 2, v[156:157]
	v_ashrrev_i32_e32 v155, 31, v154
	v_lshl_add_u64 v[134:135], s[6:7], 0, v[158:159]
	s_movk_i32 s8, 0x2000
	v_lshlrev_b64 v[136:137], 12, v[154:155]
	s_mov_b64 s[6:7], 0x2000
	v_add_co_u32_e32 v130, vcc, s8, v134
	v_lshl_add_u64 v[136:137], s[18:19], 0, v[136:137]
	s_nop 0
	v_addc_co_u32_e32 v131, vcc, 0, v135, vcc
	v_lshl_add_u64 v[142:143], v[136:137], 0, v[158:159]
	v_lshl_add_u64 v[144:145], v[134:135], 0, s[6:7]
	v_mov_b64_e32 v[244:245], v[142:143]
	s_mov_b64 s[98:99], 0x10000
	v_lshl_add_u64 v[248:249], v[244:245], 0, s[98:99]
	global_load_dwordx4 v[228:231], v[248:249], off nt
	global_load_dwordx4 v[232:235], v[248:249], off offset:16 nt
	global_load_dwordx4 v[236:239], v[248:249], off offset:512 nt
	global_load_dwordx4 v[240:243], v[248:249], off offset:528 nt
	s_mov_b64 s[98:99], 0x20000
	v_lshl_add_u64 v[248:249], v[244:245], 0, s[98:99]
	global_load_dwordx4 v[212:215], v[248:249], off nt
	global_load_dwordx4 v[216:219], v[248:249], off offset:16 nt
	global_load_dwordx4 v[220:223], v[248:249], off offset:512 nt
	global_load_dwordx4 v[224:227], v[248:249], off offset:528 nt
	global_load_dwordx4 v[130:133], v[130:131], off nt
	s_nop 0
	global_load_dwordx4 v[146:149], v[142:143], off offset:16 nt
	global_load_dwordx4 v[150:153], v[142:143], off nt
	global_load_dwordx4 v[138:141], v[144:145], off offset:16 nt
	global_load_dwordx4 v[134:137], v[144:145], off offset:512 nt
	global_load_dwordx4 v[162:165], v[142:143], off offset:512 nt
	global_load_dwordx4 v[174:177], v[142:143], off offset:528 nt
	s_nop 0
	global_load_dwordx4 v[142:145], v[144:145], off offset:528 nt
	s_waitcnt vmcnt(16)
	s_cmpk_gt_u32 s4, 0xff
	s_cbranch_scc1 .LBB0_732
	s_barrier
.LBB0_732:
	s_barrier
	v_add_u32_e32 v160, 16, v154
	v_ashrrev_i32_e32 v161, 31, v160
	v_lshlrev_b64 v[168:169], 12, v[160:161]
	v_lshl_add_u64 v[168:169], s[18:19], 0, v[168:169]
	v_lshl_add_u64 v[168:169], v[168:169], 0, v[158:159]
	v_mbcnt_hi_u32_b32 v173, -1, v1
	s_lshl_b32 s6, s17, 3
	s_add_i32 s8, s6, 0
	s_waitcnt vmcnt(0)
	v_pk_fma_f32 v[120:121], v[120:121], v[136:137], v[164:165]
	v_pk_fma_f32 v[124:125], v[124:125], v[132:133], v[152:153]
	v_pk_fma_f32 v[122:123], v[122:123], v[130:131], v[150:151]
	v_pk_fma_f32 v[128:129], v[128:129], v[140:141], v[148:149]
	v_pk_fma_f32 v[126:127], v[126:127], v[138:139], v[146:147]
	v_pk_fma_f32 v[118:119], v[118:119], v[134:135], v[162:163]
	v_pk_fma_f32 v[116:117], v[116:117], v[144:145], v[176:177]
	v_pk_fma_f32 v[114:115], v[114:115], v[142:143], v[174:175]
	v_add_u32_e32 v162, 32, v154
	s_waitcnt vmcnt(4)
	v_mov_b32_e32 v146, v228
	v_mov_b32_e32 v147, v229
	v_mov_b32_e32 v148, v230
	v_mov_b32_e32 v149, v231
	v_mov_b32_e32 v150, v232
	v_mov_b32_e32 v151, v233
	v_mov_b32_e32 v152, v234
	v_mov_b32_e32 v153, v235
	v_mov_b32_e32 v174, v236
	v_mov_b32_e32 v175, v237
	v_mov_b32_e32 v176, v238
	v_mov_b32_e32 v177, v239
	v_mov_b32_e32 v178, v240
	v_mov_b32_e32 v179, v241
	v_mov_b32_e32 v180, v242
	v_mov_b32_e32 v181, v243
	s_mov_b64 s[98:99], 0x30000
	v_lshl_add_u64 v[248:249], v[244:245], 0, s[98:99]
	global_load_dwordx4 v[228:231], v[248:249], off nt
	global_load_dwordx4 v[232:235], v[248:249], off offset:16 nt
	global_load_dwordx4 v[236:239], v[248:249], off offset:512 nt
	global_load_dwordx4 v[240:243], v[248:249], off offset:528 nt
	v_ashrrev_i32_e32 v163, 31, v162
	v_lshlrev_b64 v[164:165], 12, v[162:163]
	v_lshl_add_u64 v[164:165], s[18:19], 0, v[164:165]
	v_lshl_add_u64 v[164:165], v[164:165], 0, v[158:159]
	v_mov_b32_e32 v192, v123
	v_mov_b32_e32 v193, v124
	v_mov_b32_e32 v194, v122
	v_mov_b32_e32 v195, v125
	v_pk_add_f32 v[192:193], v[192:193], v[194:195]
	v_add_f32_e32 v197, v118, v119
	v_add_f32_e32 v192, v192, v193
	v_add_f32_e32 v199, v120, v121
	v_mov_b32_e32 v196, v114
	v_mov_b32_e32 v198, v115
	v_mov_b32_e32 v206, v117
	v_add_f32_e32 v207, 0, v192
	s_nop 0
	v_pk_fma_f32 v[112:113], v[112:113], v[132:133], v[148:149]
	v_pk_fma_f32 v[110:111], v[110:111], v[130:131], v[146:147]
	s_nop 0
	v_pk_fma_f32 v[108:109], v[108:109], v[140:141], v[152:153]
	v_pk_fma_f32 v[106:107], v[106:107], v[138:139], v[150:151]
	s_nop 0
	v_pk_fma_f32 v[72:73], v[72:73], v[136:137], v[176:177]
	v_pk_fma_f32 v[70:71], v[70:71], v[134:135], v[174:175]
	s_nop 0
	v_pk_fma_f32 v[68:69], v[68:69], v[144:145], v[180:181]
	v_pk_fma_f32 v[66:67], v[66:67], v[142:143], v[178:179]
	s_nop 0
	s_waitcnt vmcnt(4)
	v_mov_b32_e32 v146, v212
	v_mov_b32_e32 v147, v213
	v_mov_b32_e32 v148, v214
	v_mov_b32_e32 v149, v215
	v_mov_b32_e32 v150, v216
	v_mov_b32_e32 v151, v217
	v_mov_b32_e32 v152, v218
	v_mov_b32_e32 v153, v219
	v_mov_b32_e32 v174, v220
	v_mov_b32_e32 v175, v221
	v_mov_b32_e32 v176, v222
	v_mov_b32_e32 v177, v223
	v_mov_b32_e32 v178, v224
	v_mov_b32_e32 v179, v225
	v_mov_b32_e32 v180, v226
	v_mov_b32_e32 v181, v227
	s_mov_b64 s[98:99], 0x80000
	v_lshl_add_u64 v[248:249], v[244:245], 0, s[98:99]
	global_load_dwordx4 v[212:215], v[248:249], off nt
	global_load_dwordx4 v[216:219], v[248:249], off offset:16 nt
	global_load_dwordx4 v[220:223], v[248:249], off offset:512 nt
	global_load_dwordx4 v[224:227], v[248:249], off offset:528 nt
	v_add_u32_e32 v164, 48, v154
	v_ashrrev_i32_e32 v165, 31, v164
	v_lshlrev_b64 v[168:169], 12, v[164:165]
	v_lshl_add_u64 v[168:169], s[18:19], 0, v[168:169]
	v_lshl_add_u64 v[168:169], v[168:169], 0, v[158:159]
	s_nop 0
	v_pk_fma_f32 v[104:105], v[104:105], v[132:133], v[148:149]
	v_pk_fma_f32 v[102:103], v[102:103], v[130:131], v[146:147]
	s_nop 0
	v_pk_fma_f32 v[100:101], v[100:101], v[140:141], v[152:153]
	v_pk_fma_f32 v[98:99], v[98:99], v[138:139], v[150:151]
	s_nop 0
	v_pk_fma_f32 v[64:65], v[64:65], v[136:137], v[176:177]
	v_pk_fma_f32 v[62:63], v[62:63], v[134:135], v[174:175]
	s_nop 0
	v_pk_fma_f32 v[60:61], v[60:61], v[144:145], v[180:181]
	v_pk_fma_f32 v[58:59], v[58:59], v[142:143], v[178:179]
	v_add_u32_e32 v150, 0x80, v154
	s_waitcnt vmcnt(4)
; __device__ __forceinline__ float bf_lo(unsigned w) { return __uint_as_float(w << 16); }
; __device__ __forceinline__ float bf_hi(unsigned w) { return __uint_as_float(w & 0xffff0000u); }
;     __device__ __forceinline__ void fused(f32x4 (&acc)[2][2][4][2], const Unit& u, int wr, int wc, int fr, int fq, PG8_LAS unsigned char* lds, int wid, int lane) const {
;     ...
;                 for (int m = 0; m < 4; ++m) { const int r = ai * HALF + wr * 64 + m * 16 + fr; const size_t off = (size_t)(u.pm * BM + r) * 1024 + col0;
; #pragma unroll
;                     for (int bj = 0; bj < 2; ++bj) { f32x4 b0, b1;
;                         if (XIN_BF16) { const u32x4 w = *(const u32x4*)((const bf16_t*)xin + off + bj * HALF); b0 = (f32x4){bf_lo(w.x), bf_hi(w.x), bf_lo(w.y), bf_hi(w.y)}; b1 = (f32x4){bf_lo(w.z), bf_hi(w.z), bf_lo(w.w), bf_hi(w.w)}; }
;                         else { b0 = *(const f32x4*)((const float*)xin + off + bj * HALF); b1 = *(const f32x4*)((const float*)xin + off + bj * HALF + 4); }
;                         acc[ai][bj][m][0] = b0 + gv[bj][0] * acc[ai][bj][m][0]; acc[ai][bj][m][1] = b1 + gv[bj][1] * acc[ai][bj][m][1]; }
	v_mov_b32_e32 v146, v228
	v_mov_b32_e32 v147, v229
	v_mov_b32_e32 v148, v230
	v_mov_b32_e32 v149, v231
	v_mov_b32_e32 v174, v232
	v_mov_b32_e32 v175, v233
	v_mov_b32_e32 v176, v234
	v_mov_b32_e32 v177, v235
	v_mov_b32_e32 v178, v236
	v_mov_b32_e32 v179, v237
	v_mov_b32_e32 v180, v238
	v_mov_b32_e32 v181, v239
	v_mov_b32_e32 v182, v240
	v_mov_b32_e32 v183, v241
	v_mov_b32_e32 v184, v242
	v_mov_b32_e32 v185, v243
	s_mov_b64 s[98:99], 0x90000
	v_lshl_add_u64 v[248:249], v[244:245], 0, s[98:99]
	global_load_dwordx4 v[228:231], v[248:249], off nt
	global_load_dwordx4 v[232:235], v[248:249], off offset:16 nt
	global_load_dwordx4 v[236:239], v[248:249], off offset:512 nt
	global_load_dwordx4 v[240:243], v[248:249], off offset:528 nt
	v_ashrrev_i32_e32 v151, 31, v150
	v_lshlrev_b64 v[152:153], 12, v[150:151]
	v_lshl_add_u64 v[152:153], s[18:19], 0, v[152:153]
	v_lshl_add_u64 v[152:153], v[152:153], 0, v[158:159]
	s_nop 0
	v_pk_fma_f32 v[96:97], v[96:97], v[132:133], v[148:149]
	v_pk_fma_f32 v[94:95], v[94:95], v[130:131], v[146:147]
	s_nop 0
	v_pk_fma_f32 v[92:93], v[92:93], v[140:141], v[176:177]
	v_pk_fma_f32 v[90:91], v[90:91], v[138:139], v[174:175]
	s_nop 0
	v_pk_fma_f32 v[56:57], v[56:57], v[136:137], v[180:181]
	v_pk_fma_f32 v[54:55], v[54:55], v[134:135], v[178:179]
	s_nop 0
	v_pk_fma_f32 v[52:53], v[52:53], v[144:145], v[184:185]
	v_pk_fma_f32 v[50:51], v[50:51], v[142:143], v[182:183]
	v_add_u32_e32 v148, 0x90, v154
	s_waitcnt vmcnt(4)
	v_mov_b32_e32 v174, v212
	v_mov_b32_e32 v175, v213
	v_mov_b32_e32 v176, v214
	v_mov_b32_e32 v177, v215
	v_mov_b32_e32 v178, v216
	v_mov_b32_e32 v179, v217
	v_mov_b32_e32 v180, v218
	v_mov_b32_e32 v181, v219
	v_mov_b32_e32 v182, v220
	v_mov_b32_e32 v183, v221
	v_mov_b32_e32 v184, v222
	v_mov_b32_e32 v185, v223
	v_mov_b32_e32 v186, v224
	v_mov_b32_e32 v187, v225
	v_mov_b32_e32 v188, v226
	v_mov_b32_e32 v189, v227
	s_mov_b64 s[98:99], 0xa0000
	v_lshl_add_u64 v[248:249], v[244:245], 0, s[98:99]
	global_load_dwordx4 v[212:215], v[248:249], off nt
	global_load_dwordx4 v[216:219], v[248:249], off offset:16 nt
	global_load_dwordx4 v[220:223], v[248:249], off offset:512 nt
	global_load_dwordx4 v[224:227], v[248:249], off offset:528 nt
	v_ashrrev_i32_e32 v149, 31, v148
	v_lshlrev_b64 v[146:147], 12, v[148:149]
	v_lshl_add_u64 v[146:147], s[18:19], 0, v[146:147]
	v_lshl_add_u64 v[146:147], v[146:147], 0, v[158:159]
	s_nop 0
	v_pk_fma_f32 v[88:89], v[88:89], v[132:133], v[176:177]
	v_pk_fma_f32 v[86:87], v[86:87], v[130:131], v[174:175]
	s_nop 0
	v_pk_fma_f32 v[84:85], v[84:85], v[140:141], v[180:181]
	v_pk_fma_f32 v[82:83], v[82:83], v[138:139], v[178:179]
	s_nop 0
	v_pk_fma_f32 v[48:49], v[48:49], v[136:137], v[184:185]
	v_pk_fma_f32 v[46:47], v[46:47], v[134:135], v[182:183]
	s_nop 0
	v_pk_fma_f32 v[44:45], v[44:45], v[144:145], v[188:189]
	v_pk_fma_f32 v[42:43], v[42:43], v[142:143], v[186:187]
	s_nop 0
	s_waitcnt vmcnt(4)
	v_mov_b32_e32 v174, v228
	v_mov_b32_e32 v175, v229
	v_mov_b32_e32 v176, v230
	v_mov_b32_e32 v177, v231
	v_mov_b32_e32 v178, v232
	v_mov_b32_e32 v179, v233
	v_mov_b32_e32 v180, v234
	v_mov_b32_e32 v181, v235
	v_mov_b32_e32 v182, v236
	v_mov_b32_e32 v183, v237
	v_mov_b32_e32 v184, v238
	v_mov_b32_e32 v185, v239
	v_mov_b32_e32 v186, v240
	v_mov_b32_e32 v187, v241
	v_mov_b32_e32 v188, v242
	v_mov_b32_e32 v189, v243
	s_mov_b64 s[98:99], 0xb0000
	v_lshl_add_u64 v[248:249], v[244:245], 0, s[98:99]
	global_load_dwordx4 v[228:231], v[248:249], off nt
	global_load_dwordx4 v[232:235], v[248:249], off offset:16 nt
	global_load_dwordx4 v[236:239], v[248:249], off offset:512 nt
	global_load_dwordx4 v[240:243], v[248:249], off offset:528 nt
	v_add_u32_e32 v146, 0xa0, v154
	v_ashrrev_i32_e32 v147, 31, v146
	v_lshlrev_b64 v[152:153], 12, v[146:147]
	v_lshl_add_u64 v[152:153], s[18:19], 0, v[152:153]
	v_lshl_add_u64 v[152:153], v[152:153], 0, v[158:159]
	s_nop 0
	v_pk_fma_f32 v[80:81], v[80:81], v[132:133], v[176:177]
	v_pk_fma_f32 v[78:79], v[78:79], v[130:131], v[174:175]
	s_nop 0
	v_pk_fma_f32 v[76:77], v[76:77], v[140:141], v[180:181]
	v_pk_fma_f32 v[74:75], v[74:75], v[138:139], v[178:179]
	s_nop 0
	v_pk_fma_f32 v[40:41], v[40:41], v[136:137], v[184:185]
	v_pk_fma_f32 v[38:39], v[38:39], v[134:135], v[182:183]
	s_nop 0
	v_pk_fma_f32 v[36:37], v[36:37], v[144:145], v[188:189]
	v_pk_fma_f32 v[34:35], v[34:35], v[142:143], v[186:187]
	s_nop 0
	s_waitcnt vmcnt(4)
; __device__ __forceinline__ float bf_lo(unsigned w) { return __uint_as_float(w << 16); }
; __device__ __forceinline__ float bf_hi(unsigned w) { return __uint_as_float(w & 0xffff0000u); }
;     template <class Mid> __device__ __forceinline__ bool run(const f32x4 (&v)[2][2][4][2], const Unit& u, int wr, int wc, int fr, int fq, PG8_LAS unsigned char* lds, int wid, int lane, const Mid& mid) const {
;     ...
;         for (int ai = 0; ai < 2; ++ai)
; #pragma unroll
;             for (int m = 0; m < 4; ++m) {
;                 float s = 0.f;
; #pragma unroll
;                 for (int bj = 0; bj < 2; ++bj)
; #pragma unroll
;                     for (int n = 0; n < 2; ++n) { const f32x4 x = v[ai][bj][m][n]; s += (x[0] + x[1]) + (x[2] + x[3]); }
;                 s += __shfl_xor(s, 16); s += __shfl_xor(s, 32);
;                 const float mw = s * (1.0f / 64.0f); float q = 0.f;
; #pragma unroll
;                 for (int bj = 0; bj < 2; ++bj)
; #pragma unroll
;                     for (int n = 0; n < 2; ++n) { const f32x4 d = v[ai][bj][m][n] - mw; q += (d[0] * d[0] + d[1] * d[1]) + (d[2] * d[2] + d[3] * d[3]); }
;                 q += __shfl_xor(q, 16); q += __shfl_xor(q, 32);
;                 if (fq == 0) P[(ai * HALF + wr * 64 + m * 16 + fr) * 4 + wc] = (f32x2v){mw, q};
;     __device__ __forceinline__ void fused(f32x4 (&acc)[2][2][4][2], const Unit& u, int wr, int wc, int fr, int fq, PG8_LAS unsigned char* lds, int wid, int lane) const {
;     ...
;                     for (int bj = 0; bj < 2; ++bj) { f32x4 b0, b1;
;                         if (XIN_BF16) { const u32x4 w = *(const u32x4*)((const bf16_t*)xin + off + bj * HALF); b0 = (f32x4){bf_lo(w.x), bf_hi(w.x), bf_lo(w.y), bf_hi(w.y)}; b1 = (f32x4){bf_lo(w.z), bf_hi(w.z), bf_lo(w.w), bf_hi(w.w)}; }
;                         else { b0 = *(const f32x4*)((const float*)xin + off + bj * HALF); b1 = *(const f32x4*)((const float*)xin + off + bj * HALF + 4); }
;                         acc[ai][bj][m][0] = b0 + gv[bj][0] * acc[ai][bj][m][0]; acc[ai][bj][m][1] = b1 + gv[bj][1] * acc[ai][bj][m][1]; }
	v_mov_b32_e32 v174, v212
	v_mov_b32_e32 v175, v213
	v_mov_b32_e32 v176, v214
	v_mov_b32_e32 v177, v215
	v_mov_b32_e32 v178, v216
	v_mov_b32_e32 v179, v217
	v_mov_b32_e32 v180, v218
	v_mov_b32_e32 v181, v219
	v_mov_b32_e32 v182, v220
	v_mov_b32_e32 v183, v221
	v_mov_b32_e32 v184, v222
	v_mov_b32_e32 v185, v223
	v_mov_b32_e32 v186, v224
	v_mov_b32_e32 v187, v225
	v_mov_b32_e32 v188, v226
	v_mov_b32_e32 v189, v227
	v_and_b32_e32 v153, 64, v173
	v_xor_b32_e32 v152, 16, v173
	v_add_u32_e32 v208, 64, v153
	v_cmp_lt_i32_e32 vcc, v152, v208
	s_nop 0
	v_pk_fma_f32 v[32:33], v[32:33], v[132:133], v[176:177]
	v_cndmask_b32_e32 v152, v173, v152, vcc
	v_lshlrev_b32_e32 v167, 2, v152
	v_add_u32_e32 v152, 0xb0, v154
	v_ashrrev_i32_e32 v153, 31, v152
	v_lshlrev_b64 v[168:169], 12, v[152:153]
	v_lshl_add_u64 v[168:169], s[18:19], 0, v[168:169]
	v_lshl_add_u64 v[168:169], v[168:169], 0, v[158:159]
	v_pk_fma_f32 v[30:31], v[30:31], v[130:131], v[174:175]
	s_nop 0
	v_pk_fma_f32 v[28:29], v[28:29], v[140:141], v[180:181]
	v_pk_fma_f32 v[26:27], v[26:27], v[138:139], v[178:179]
	s_nop 0
	v_pk_fma_f32 v[24:25], v[24:25], v[136:137], v[184:185]
	v_pk_fma_f32 v[22:23], v[22:23], v[134:135], v[182:183]
	s_nop 0
	v_pk_fma_f32 v[20:21], v[20:21], v[144:145], v[188:189]
	v_pk_fma_f32 v[18:19], v[18:19], v[142:143], v[186:187]
	v_mov_b32_e32 v174, v127
	s_waitcnt vmcnt(0)
	v_mov_b32_e32 v176, v232
	v_mov_b32_e32 v177, v233
	v_mov_b32_e32 v178, v234
	v_mov_b32_e32 v179, v235
	v_mov_b32_e32 v180, v228
	v_mov_b32_e32 v181, v229
	v_mov_b32_e32 v182, v230
	v_mov_b32_e32 v183, v231
	v_mov_b32_e32 v184, v240
	v_mov_b32_e32 v185, v241
	v_mov_b32_e32 v186, v242
	v_mov_b32_e32 v187, v243
	v_mov_b32_e32 v188, v236
	v_mov_b32_e32 v189, v237
	v_mov_b32_e32 v190, v238
	v_mov_b32_e32 v191, v239
	v_mov_b32_e32 v175, v128
	v_mov_b32_e32 v168, v126
	v_mov_b32_e32 v169, v129
	v_pk_add_f32 v[168:169], v[174:175], v[168:169]
	v_pk_add_f32 v[174:175], v[196:197], v[198:199]
	v_pk_add_f32 v[168:169], v[168:169], v[168:169] op_sel_hi:[0,1]
	v_mov_b32_e32 v168, v116
	v_pk_add_f32 v[168:169], v[168:169], v[206:207]
	s_nop 0
	v_pk_fma_f32 v[12:13], v[12:13], v[140:141], v[178:179]
	v_pk_add_f32 v[168:169], v[174:175], v[168:169]
	s_nop 0
	v_pk_fma_f32 v[16:17], v[16:17], v[132:133], v[182:183]
	v_add_f32_e32 v168, v168, v169
	ds_bpermute_b32 v174, v167, v168
	v_xor_b32_e32 v169, 32, v173
	v_cmp_lt_i32_e32 vcc, v169, v208
	v_pk_fma_f32 v[14:15], v[14:15], v[130:131], v[180:181]
	v_pk_fma_f32 v[10:11], v[10:11], v[138:139], v[176:177]
	v_cndmask_b32_e32 v169, v173, v169, vcc
	v_lshlrev_b32_e32 v169, 2, v169
	s_waitcnt lgkmcnt(0)
	v_add_f32_e32 v168, v168, v174
	ds_bpermute_b32 v173, v169, v168
	s_nop 0
	v_pk_fma_f32 v[8:9], v[8:9], v[136:137], v[190:191]
	v_pk_fma_f32 v[6:7], v[6:7], v[134:135], v[188:189]
	v_pk_fma_f32 v[4:5], v[4:5], v[144:145], v[186:187]
	v_pk_fma_f32 v[2:3], v[2:3], v[142:143], v[184:185]
	s_waitcnt lgkmcnt(0)
	v_add_f32_e32 v173, v168, v173
	v_fmamk_f32 v174, v173, 0xbc800000, v125
	v_fmamk_f32 v192, v173, 0xbc800000, v123
	v_fmamk_f32 v194, v173, 0xbc800000, v129
	v_fmamk_f32 v196, v173, 0xbc800000, v127
	v_fmamk_f32 v168, v173, 0xbc800000, v124
	v_fmamk_f32 v175, v173, 0xbc800000, v122
	v_fmamk_f32 v193, v173, 0xbc800000, v128
	v_fmamk_f32 v195, v173, 0xbc800000, v126
	v_fmamk_f32 v198, v173, 0xbc800000, v121
	v_fmamk_f32 v206, v173, 0xbc800000, v119
	v_mul_f32_e32 v192, v192, v192
	v_mul_f32_e32 v174, v174, v174
	v_mul_f32_e32 v196, v196, v196
	v_mul_f32_e32 v194, v194, v194
	v_fmamk_f32 v197, v173, 0xbc800000, v120
	v_fmamk_f32 v199, v173, 0xbc800000, v118
	v_fmamk_f32 v208, v173, 0xbc800000, v117
	v_fmamk_f32 v210, v173, 0xbc800000, v115
	v_mul_f32_e32 v206, v206, v206
	v_mul_f32_e32 v198, v198, v198
	v_fmac_f32_e32 v192, v175, v175
	v_fmac_f32_e32 v174, v168, v168
	v_fmac_f32_e32 v196, v195, v195
	v_fmac_f32_e32 v194, v193, v193
	v_fmamk_f32 v207, v173, 0xbc800000, v116
	v_fmamk_f32 v209, v173, 0xbc800000, v114
	v_mul_f32_e32 v210, v210, v210
	v_mul_f32_e32 v208, v208, v208
	v_fmac_f32_e32 v206, v199, v199
	v_fmac_f32_e32 v198, v197, v197
	v_add_f32_e32 v168, v192, v174
	v_add_f32_e32 v174, v196, v194
	v_fmac_f32_e32 v210, v209, v209
	v_fmac_f32_e32 v208, v207, v207
	v_add_f32_e32 v175, v206, v198
	v_add_f32_e32 v168, v168, v174
	v_add_f32_e32 v192, v210, v208
	v_add_f32_e32 v168, v175, v168
	v_add_f32_e32 v174, v192, v168
	ds_bpermute_b32 v175, v167, v174
	v_and_b32_e32 v168, 63, v166
	v_cmp_gt_u32_e32 vcc, 16, v168
	s_waitcnt lgkmcnt(0)
	v_add_f32_e32 v174, v174, v175
	ds_bpermute_b32 v175, v169, v174
	s_and_saveexec_b64 s[6:7], vcc
	s_cbranch_execz .LBB0_734
	s_lshl_b32 s9, s23, 11
	s_add_i32 s9, s8, s9
	v_mul_f32_e32 v130, 0x3c800000, v173
	s_waitcnt lgkmcnt(0)
	v_add_f32_e32 v131, v174, v175
	v_lshl_add_u32 v132, v171, 5, s9
	ds_write_b64 v132, v[130:131]
